# H SwiGLU epilogue: permlane16_swap pairs the lane's two 8-byte row pieces into one dwordx4 store (16 -> 8 stores per tile)
# speedup vs baseline: 1.0167x; 1.0090x over previous
.LBB0_120:
	v_bfe_u32 v16, v6, 4, 2
	v_and_b32_e32 v7, 15, v6
	v_lshlrev_b32_e32 v17, 4, v16
	v_lshlrev_b32_e32 v6, 2, v6
	s_lshl_b32 s0, s0, 5
	v_mov_b32_e32 v131, v189
	v_lshl_or_b32 v138, s2, 6, v7
	v_lshl_or_b32 v7, v7, 6, v17
	s_lshl_b32 s2, s2, 13
	v_and_b32_e32 v6, 32, v6
	s_and_b32 s0, s0, 0x60
	v_lshl_add_u64 v[8:9], s[16:17], 0, v[130:131]
	v_mov_b32_e32 v129, v189
	v_readlane_b32 s10, v253, 23
	v_bitop3_b32 v17, v7, s2, v6 bitop3:0xde
	s_lshl_b32 s2, s0, 7
	v_lshl_add_u64 v[10:11], s[16:17], 0, v[128:129]
	v_readlane_b32 s11, v253, 24
	v_bitop3_b32 v139, v7, s2, v6 bitop3:0xde
	s_add_i32 m0, s24, 0x18000
	v_lshl_add_u64 v[6:7], v[8:9], 0, s[92:93]
	v_lshl_add_u64 v[12:13], s[10:11], 0, v[130:131]
	s_waitcnt vmcnt(4)
	s_barrier
	global_load_lds_dwordx4 v[6:7], off
	v_lshl_add_u64 v[6:7], v[10:11], 0, s[92:93]
	s_add_i32 m0, s24, 0x1a000
	s_add_i32 s28, s24, 0x8000
	s_add_i32 s29, s24, 0xa000
	v_lshl_add_u64 v[14:15], s[10:11], 0, v[128:129]
	global_load_lds_dwordx4 v[6:7], off
	v_lshl_add_u64 v[6:7], v[12:13], 0, s[92:93]
	s_mov_b32 m0, s28
	s_add_u32 s2, s16, 0x40080
	global_load_lds_dwordx4 v[6:7], off
	v_lshl_add_u64 v[6:7], v[14:15], 0, s[92:93]
	s_mov_b32 m0, s29
	s_addc_u32 s3, s17, 0
	global_load_lds_dwordx4 v[6:7], off
	s_add_i32 m0, s24, 0x1c000
	v_lshl_add_u64 v[6:7], s[2:3], 0, v[130:131]
	global_load_lds_dwordx4 v[6:7], off
	v_lshl_add_u64 v[6:7], s[2:3], 0, v[128:129]
	s_add_i32 m0, s24, 0x1e000
	v_readlane_b32 s2, v253, 21
	global_load_lds_dwordx4 v[6:7], off
	v_lshlrev_b32_e32 v7, 14, v3
	v_and_b32_e32 v7, 0xffff8000, v7
	v_lshl_add_u32 v4, v4, 11, v7
	v_and_b32_e32 v3, 1, v3
	v_lshl_or_b32 v3, v3, 6, v4
	v_lshl_add_u32 v132, v5, 1, v3
	v_lshlrev_b32_e32 v3, 14, v0
	v_and_b32_e32 v3, 0xffff8000, v3
	s_waitcnt vmcnt(6)
	v_lshl_add_u32 v1, v1, 11, v3
	v_and_b32_e32 v0, 1, v0
	v_lshlrev_b32_e32 v6, 2, v16
	v_lshl_or_b32 v0, v0, 6, v1
	v_readlane_b32 s3, v253, 22
	v_mov_b32_e32 v133, v189
	v_lshl_add_u32 v134, v2, 1, v0
	v_mov_b32_e32 v135, v189
	s_mov_b32 s30, 0
	v_add_u32_e32 v140, 0, v17
	s_lshl_b32 s0, s0, 1
	v_and_b32_e32 v188, 8, v6
	v_and_b32_e32 v250, 4, v6
	v_lshlrev_b32_e32 v188, 1, v188
	v_lshl_or_b32 v188, v250, 3, v188
	v_readlane_b32 s31, v253, 18
	s_mov_b32 s33, s2
	s_mov_b64 s[2:3], s[10:11]
	s_barrier

.LBB0_124:
	s_add_u32 s16, s2, 0xfffc0080
	s_addc_u32 s17, s3, -1
	s_add_i32 s39, 0, 0x10000
	v_add_u32_e32 v136, s39, v139
	ds_read_b128 v[142:145], v136
	ds_read_b128 v[146:149], v136 offset:1024
	ds_read_b128 v[150:153], v136 offset:2048
	ds_read_b128 v[154:157], v136 offset:3072
	s_cmp_eq_u32 s38, 12
	s_cselect_b32 s19, s5, s17
	s_cselect_b32 s18, s34, s16
	s_cselect_b32 s17, s9, s37
	s_cselect_b32 s16, s35, s36
	v_lshl_add_u64 v[136:137], s[2:3], 0, v[132:133]
	s_add_i32 m0, s24, 0xc000
	ds_read_b128 v[158:161], v140
	ds_read_b128 v[162:165], v140 offset:1024
	ds_read_b128 v[166:169], v140 offset:2048
	ds_read_b128 v[170:173], v140 offset:3072
	ds_read_b128 v[174:177], v140 offset:4096
	ds_read_b128 v[178:181], v140 offset:5120
	ds_read_b128 v[182:185], v140 offset:6144
	ds_read_b128 v[190:193], v140 offset:7168
	global_load_lds_dwordx4 v[136:137], off
	v_lshl_add_u64 v[136:137], s[2:3], 0, v[134:135]
	s_add_i32 m0, s24, 0xe000
	s_nop 0
	global_load_lds_dwordx4 v[136:137], off
	s_waitcnt lgkmcnt(8)
	s_barrier
	s_waitcnt lgkmcnt(0)
	s_setprio 1
	s_waitcnt lgkmcnt(0)
	v_mfma_f32_16x16x32_bf16 v[124:127], v[142:145], v[158:161], v[124:127]
	v_mfma_f32_16x16x32_bf16 v[116:119], v[150:153], v[158:161], v[116:119]
	v_mfma_f32_16x16x32_bf16 v[108:111], v[142:145], v[166:169], v[108:111]
	v_mfma_f32_16x16x32_bf16 v[100:103], v[150:153], v[166:169], v[100:103]
	v_mfma_f32_16x16x32_bf16 v[92:95], v[142:145], v[174:177], v[92:95]
	v_mfma_f32_16x16x32_bf16 v[84:87], v[150:153], v[174:177], v[84:87]
	v_mfma_f32_16x16x32_bf16 v[76:79], v[142:145], v[182:185], v[76:79]
	v_mfma_f32_16x16x32_bf16 v[68:71], v[150:153], v[182:185], v[68:71]
	v_mfma_f32_16x16x32_bf16 v[124:127], v[146:149], v[162:165], v[124:127]
	v_mfma_f32_16x16x32_bf16 v[116:119], v[154:157], v[162:165], v[116:119]
	v_mfma_f32_16x16x32_bf16 v[108:111], v[146:149], v[170:173], v[108:111]
	v_mfma_f32_16x16x32_bf16 v[100:103], v[154:157], v[170:173], v[100:103]
	v_mfma_f32_16x16x32_bf16 v[92:95], v[146:149], v[178:181], v[92:95]
	v_mfma_f32_16x16x32_bf16 v[84:87], v[154:157], v[178:181], v[84:87]
	v_mfma_f32_16x16x32_bf16 v[76:79], v[146:149], v[190:193], v[76:79]
	v_mfma_f32_16x16x32_bf16 v[68:71], v[154:157], v[190:193], v[68:71]
	s_setprio 0
	s_barrier
	s_add_i32 s42, 0, 0x14000
	v_add_u32_e32 v136, s42, v139
	s_add_i32 s39, s39, s23
	ds_read_b128 v[194:197], v136
	ds_read_b128 v[198:201], v136 offset:1024
	ds_read_b128 v[216:219], v136 offset:2048
	ds_read_b128 v[220:223], v136 offset:3072
	v_lshl_add_u64 v[136:137], s[16:17], 0, v[130:131]
	s_mov_b32 m0, s39
	v_lshl_add_u64 v[186:187], s[16:17], 0, v[128:129]
	global_load_lds_dwordx4 v[136:137], off
	s_add_i32 m0, s39, 0x2000
	s_nop 0
	global_load_lds_dwordx4 v[186:187], off
	s_barrier
	s_waitcnt lgkmcnt(0)
	s_setprio 1
	s_waitcnt lgkmcnt(0)
	v_mfma_f32_16x16x32_bf16 v[120:123], v[194:197], v[158:161], v[120:123]
	v_mfma_f32_16x16x32_bf16 v[112:115], v[216:219], v[158:161], v[112:115]
	v_mfma_f32_16x16x32_bf16 v[104:107], v[194:197], v[166:169], v[104:107]
	v_mfma_f32_16x16x32_bf16 v[96:99], v[216:219], v[166:169], v[96:99]
	v_mfma_f32_16x16x32_bf16 v[88:91], v[194:197], v[174:177], v[88:91]
	v_mfma_f32_16x16x32_bf16 v[80:83], v[216:219], v[174:177], v[80:83]
	v_mfma_f32_16x16x32_bf16 v[72:75], v[194:197], v[182:185], v[72:75]
	v_mfma_f32_16x16x32_bf16 v[64:67], v[216:219], v[182:185], v[64:67]
	v_mfma_f32_16x16x32_bf16 v[120:123], v[198:201], v[162:165], v[120:123]
	v_mfma_f32_16x16x32_bf16 v[112:115], v[220:223], v[162:165], v[112:115]
	v_mfma_f32_16x16x32_bf16 v[104:107], v[198:201], v[170:173], v[104:107]
	v_mfma_f32_16x16x32_bf16 v[96:99], v[220:223], v[170:173], v[96:99]
	v_mfma_f32_16x16x32_bf16 v[88:91], v[198:201], v[178:181], v[88:91]
	v_mfma_f32_16x16x32_bf16 v[80:83], v[220:223], v[178:181], v[80:83]
	v_mfma_f32_16x16x32_bf16 v[72:75], v[198:201], v[190:193], v[72:75]
	v_mfma_f32_16x16x32_bf16 v[64:67], v[220:223], v[190:193], v[64:67]
	s_setprio 0
	s_mov_b32 m0, s24
	v_lshl_add_u64 v[202:203], s[18:19], 0, v[130:131]
	s_barrier
	ds_read_b128 v[158:161], v140 offset:16384
	ds_read_b128 v[162:165], v140 offset:17408
	ds_read_b128 v[166:169], v140 offset:18432
	ds_read_b128 v[170:173], v140 offset:19456
	ds_read_b128 v[174:177], v140 offset:20480
	ds_read_b128 v[178:181], v140 offset:21504
	ds_read_b128 v[182:185], v140 offset:22528
	ds_read_b128 v[190:193], v140 offset:23552
	global_load_lds_dwordx4 v[202:203], off
	v_lshl_add_u64 v[224:225], s[18:19], 0, v[128:129]
	s_mov_b32 m0, s25
	s_nop 0
	global_load_lds_dwordx4 v[224:225], off
	s_barrier
	s_waitcnt lgkmcnt(0)
	s_setprio 1
	s_waitcnt lgkmcnt(0)
	v_mfma_f32_16x16x32_bf16 v[60:63], v[142:145], v[158:161], v[60:63]
	v_mfma_f32_16x16x32_bf16 v[52:55], v[150:153], v[158:161], v[52:55]
	v_mfma_f32_16x16x32_bf16 v[44:47], v[142:145], v[166:169], v[44:47]
	v_mfma_f32_16x16x32_bf16 v[36:39], v[150:153], v[166:169], v[36:39]
	v_mfma_f32_16x16x32_bf16 v[28:31], v[142:145], v[174:177], v[28:31]
	v_mfma_f32_16x16x32_bf16 v[20:23], v[150:153], v[174:177], v[20:23]
	v_mfma_f32_16x16x32_bf16 v[12:15], v[142:145], v[182:185], v[12:15]
	v_mfma_f32_16x16x32_bf16 v[4:7], v[150:153], v[182:185], v[4:7]
	v_mfma_f32_16x16x32_bf16 v[60:63], v[146:149], v[162:165], v[60:63]
	v_mfma_f32_16x16x32_bf16 v[52:55], v[154:157], v[162:165], v[52:55]
	v_mfma_f32_16x16x32_bf16 v[44:47], v[146:149], v[170:173], v[44:47]
	v_mfma_f32_16x16x32_bf16 v[36:39], v[154:157], v[170:173], v[36:39]
	v_mfma_f32_16x16x32_bf16 v[28:31], v[146:149], v[178:181], v[28:31]
	v_mfma_f32_16x16x32_bf16 v[20:23], v[154:157], v[178:181], v[20:23]
	v_mfma_f32_16x16x32_bf16 v[12:15], v[146:149], v[190:193], v[12:15]
	v_mfma_f32_16x16x32_bf16 v[4:7], v[154:157], v[190:193], v[4:7]
	s_setprio 0
	s_barrier
	s_add_u32 s40, s16, 0x40000
	s_addc_u32 s41, s17, 0
	s_add_i32 s39, s42, s23
	v_lshl_add_u64 v[142:143], s[40:41], 0, v[130:131]
	s_mov_b32 m0, s39
	s_nop 0
	global_load_lds_dwordx4 v[142:143], off
	v_lshl_add_u64 v[142:143], s[40:41], 0, v[128:129]
	s_add_i32 m0, s39, 0x2000
	s_nop 0
	global_load_lds_dwordx4 v[142:143], off
	s_waitcnt vmcnt(6)
	s_barrier
	s_setprio 1
	v_mfma_f32_16x16x32_bf16 v[56:59], v[194:197], v[158:161], v[56:59]
	v_mfma_f32_16x16x32_bf16 v[48:51], v[216:219], v[158:161], v[48:51]
	v_mfma_f32_16x16x32_bf16 v[40:43], v[194:197], v[166:169], v[40:43]
	v_mfma_f32_16x16x32_bf16 v[32:35], v[216:219], v[166:169], v[32:35]
	v_mfma_f32_16x16x32_bf16 v[24:27], v[194:197], v[174:177], v[24:27]
	v_mfma_f32_16x16x32_bf16 v[16:19], v[216:219], v[174:177], v[16:19]
	v_mfma_f32_16x16x32_bf16 v[8:11], v[194:197], v[182:185], v[8:11]
	v_mfma_f32_16x16x32_bf16 v[0:3], v[216:219], v[182:185], v[0:3]
	v_mfma_f32_16x16x32_bf16 v[56:59], v[198:201], v[162:165], v[56:59]
	v_mfma_f32_16x16x32_bf16 v[48:51], v[220:223], v[162:165], v[48:51]
	v_mfma_f32_16x16x32_bf16 v[40:43], v[198:201], v[170:173], v[40:43]
	v_mfma_f32_16x16x32_bf16 v[32:35], v[220:223], v[170:173], v[32:35]
	v_mfma_f32_16x16x32_bf16 v[24:27], v[198:201], v[178:181], v[24:27]
	v_mfma_f32_16x16x32_bf16 v[16:19], v[220:223], v[178:181], v[16:19]
	v_mfma_f32_16x16x32_bf16 v[8:11], v[198:201], v[190:193], v[8:11]
	v_mfma_f32_16x16x32_bf16 v[0:3], v[220:223], v[190:193], v[0:3]
	s_setprio 0
	s_add_i32 s39, 0, 0x18000
	v_add_u32_e32 v141, s39, v139
	s_barrier
	ds_read_b128 v[142:145], v141
	ds_read_b128 v[146:149], v141 offset:1024
	ds_read_b128 v[150:153], v141 offset:2048
	ds_read_b128 v[154:157], v141 offset:3072
	s_add_u32 s18, s18, 0x40000
	s_addc_u32 s19, s19, 0
	s_mov_b32 m0, s26
	v_lshl_add_u64 v[194:195], s[18:19], 0, v[130:131]
	ds_read_b128 v[158:161], v140 offset:32768
	ds_read_b128 v[162:165], v140 offset:33792
	ds_read_b128 v[166:169], v140 offset:34816
	ds_read_b128 v[170:173], v140 offset:35840
	ds_read_b128 v[174:177], v140 offset:36864
	ds_read_b128 v[178:181], v140 offset:37888
	ds_read_b128 v[182:185], v140 offset:38912
	ds_read_b128 v[190:193], v140 offset:39936
	global_load_lds_dwordx4 v[194:195], off
	v_lshl_add_u64 v[194:195], s[18:19], 0, v[128:129]
	s_mov_b32 m0, s27
	s_nop 0
	global_load_lds_dwordx4 v[194:195], off
	s_waitcnt lgkmcnt(8)
	s_barrier
	s_waitcnt lgkmcnt(0)
	s_setprio 1
	s_waitcnt lgkmcnt(0)
	v_mfma_f32_16x16x32_bf16 v[124:127], v[142:145], v[158:161], v[124:127]
	v_mfma_f32_16x16x32_bf16 v[116:119], v[150:153], v[158:161], v[116:119]
	v_mfma_f32_16x16x32_bf16 v[108:111], v[142:145], v[166:169], v[108:111]
	v_mfma_f32_16x16x32_bf16 v[100:103], v[150:153], v[166:169], v[100:103]
	v_mfma_f32_16x16x32_bf16 v[92:95], v[142:145], v[174:177], v[92:95]
	v_mfma_f32_16x16x32_bf16 v[84:87], v[150:153], v[174:177], v[84:87]
	v_mfma_f32_16x16x32_bf16 v[76:79], v[142:145], v[182:185], v[76:79]
	v_mfma_f32_16x16x32_bf16 v[68:71], v[150:153], v[182:185], v[68:71]
	v_mfma_f32_16x16x32_bf16 v[124:127], v[146:149], v[162:165], v[124:127]
	v_mfma_f32_16x16x32_bf16 v[116:119], v[154:157], v[162:165], v[116:119]
	v_mfma_f32_16x16x32_bf16 v[108:111], v[146:149], v[170:173], v[108:111]
	v_mfma_f32_16x16x32_bf16 v[100:103], v[154:157], v[170:173], v[100:103]
	v_mfma_f32_16x16x32_bf16 v[92:95], v[146:149], v[178:181], v[92:95]
	v_mfma_f32_16x16x32_bf16 v[84:87], v[154:157], v[178:181], v[84:87]
	v_mfma_f32_16x16x32_bf16 v[76:79], v[146:149], v[190:193], v[76:79]
	v_mfma_f32_16x16x32_bf16 v[68:71], v[154:157], v[190:193], v[68:71]
	s_setprio 0
	s_barrier
	s_add_i32 s18, 0, 0x1c000
	s_add_i32 s19, s39, s23
	v_add_u32_e32 v141, s18, v139
	v_lshl_add_u64 v[136:137], v[136:137], 0, s[92:93]
	s_mov_b32 m0, s19
	ds_read_b128 v[194:197], v141
	ds_read_b128 v[198:201], v141 offset:1024
	ds_read_b128 v[216:219], v141 offset:2048
	ds_read_b128 v[220:223], v141 offset:3072
	global_load_lds_dwordx4 v[136:137], off
	v_lshl_add_u64 v[136:137], v[186:187], 0, s[92:93]
	s_add_i32 m0, s19, 0x2000
	s_nop 0
	global_load_lds_dwordx4 v[136:137], off
	s_barrier
	s_waitcnt lgkmcnt(0)
	s_setprio 1
	s_waitcnt lgkmcnt(0)
	v_mfma_f32_16x16x32_bf16 v[120:123], v[194:197], v[158:161], v[120:123]
	v_mfma_f32_16x16x32_bf16 v[112:115], v[216:219], v[158:161], v[112:115]
	v_mfma_f32_16x16x32_bf16 v[104:107], v[194:197], v[166:169], v[104:107]
	v_mfma_f32_16x16x32_bf16 v[96:99], v[216:219], v[166:169], v[96:99]
	v_mfma_f32_16x16x32_bf16 v[88:91], v[194:197], v[174:177], v[88:91]
	v_mfma_f32_16x16x32_bf16 v[80:83], v[216:219], v[174:177], v[80:83]
	v_mfma_f32_16x16x32_bf16 v[72:75], v[194:197], v[182:185], v[72:75]
	v_mfma_f32_16x16x32_bf16 v[64:67], v[216:219], v[182:185], v[64:67]
	v_mfma_f32_16x16x32_bf16 v[120:123], v[198:201], v[162:165], v[120:123]
	v_mfma_f32_16x16x32_bf16 v[112:115], v[220:223], v[162:165], v[112:115]
	v_mfma_f32_16x16x32_bf16 v[104:107], v[198:201], v[170:173], v[104:107]
	v_mfma_f32_16x16x32_bf16 v[96:99], v[220:223], v[170:173], v[96:99]
	v_mfma_f32_16x16x32_bf16 v[88:91], v[198:201], v[178:181], v[88:91]
	v_mfma_f32_16x16x32_bf16 v[80:83], v[220:223], v[178:181], v[80:83]
	v_mfma_f32_16x16x32_bf16 v[72:75], v[198:201], v[190:193], v[72:75]
	v_mfma_f32_16x16x32_bf16 v[64:67], v[220:223], v[190:193], v[64:67]
	s_setprio 0
	s_mov_b32 m0, s28
	v_lshl_add_u64 v[136:137], v[202:203], 0, s[92:93]
	s_barrier
	ds_read_b128 v[158:161], v140 offset:49152
	ds_read_b128 v[162:165], v140 offset:50176
	ds_read_b128 v[166:169], v140 offset:51200
	ds_read_b128 v[170:173], v140 offset:52224
	ds_read_b128 v[174:177], v140 offset:53248
	ds_read_b128 v[178:181], v140 offset:54272
	ds_read_b128 v[182:185], v140 offset:55296
	ds_read_b128 v[190:193], v140 offset:56320
	global_load_lds_dwordx4 v[136:137], off
	v_lshl_add_u64 v[136:137], v[224:225], 0, s[92:93]
	s_mov_b32 m0, s29
	s_nop 0
	global_load_lds_dwordx4 v[136:137], off
	s_barrier
	s_waitcnt lgkmcnt(0)
	s_setprio 1
	s_waitcnt lgkmcnt(0)
	v_mfma_f32_16x16x32_bf16 v[60:63], v[142:145], v[158:161], v[60:63]
	v_mfma_f32_16x16x32_bf16 v[52:55], v[150:153], v[158:161], v[52:55]
	v_mfma_f32_16x16x32_bf16 v[44:47], v[142:145], v[166:169], v[44:47]
	v_mfma_f32_16x16x32_bf16 v[36:39], v[150:153], v[166:169], v[36:39]
	v_mfma_f32_16x16x32_bf16 v[28:31], v[142:145], v[174:177], v[28:31]
	v_mfma_f32_16x16x32_bf16 v[20:23], v[150:153], v[174:177], v[20:23]
	v_mfma_f32_16x16x32_bf16 v[12:15], v[142:145], v[182:185], v[12:15]
	v_mfma_f32_16x16x32_bf16 v[4:7], v[150:153], v[182:185], v[4:7]
	v_mfma_f32_16x16x32_bf16 v[60:63], v[146:149], v[162:165], v[60:63]
	v_mfma_f32_16x16x32_bf16 v[52:55], v[154:157], v[162:165], v[52:55]
	v_mfma_f32_16x16x32_bf16 v[44:47], v[146:149], v[170:173], v[44:47]
	v_mfma_f32_16x16x32_bf16 v[36:39], v[154:157], v[170:173], v[36:39]
	v_mfma_f32_16x16x32_bf16 v[28:31], v[146:149], v[178:181], v[28:31]
	v_mfma_f32_16x16x32_bf16 v[20:23], v[154:157], v[178:181], v[20:23]
	v_mfma_f32_16x16x32_bf16 v[12:15], v[146:149], v[190:193], v[12:15]
	v_mfma_f32_16x16x32_bf16 v[4:7], v[154:157], v[190:193], v[4:7]
	s_setprio 0
	s_barrier
	s_add_u32 s16, s16, 0x40080
	s_addc_u32 s17, s17, 0
	s_add_i32 s18, s18, s23
	v_lshl_add_u64 v[136:137], s[16:17], 0, v[130:131]
	s_mov_b32 m0, s18
	s_nop 0
	global_load_lds_dwordx4 v[136:137], off
	v_lshl_add_u64 v[136:137], s[16:17], 0, v[128:129]
	s_add_i32 m0, s18, 0x2000
	s_nop 0
	global_load_lds_dwordx4 v[136:137], off
	s_waitcnt vmcnt(6)
	s_barrier
	s_setprio 1
	v_mfma_f32_16x16x32_bf16 v[56:59], v[194:197], v[158:161], v[56:59]
	v_mfma_f32_16x16x32_bf16 v[48:51], v[216:219], v[158:161], v[48:51]
	v_mfma_f32_16x16x32_bf16 v[40:43], v[194:197], v[166:169], v[40:43]
	v_mfma_f32_16x16x32_bf16 v[32:35], v[216:219], v[166:169], v[32:35]
	v_mfma_f32_16x16x32_bf16 v[24:27], v[194:197], v[174:177], v[24:27]
	v_mfma_f32_16x16x32_bf16 v[16:19], v[216:219], v[174:177], v[16:19]
	v_mfma_f32_16x16x32_bf16 v[8:11], v[194:197], v[182:185], v[8:11]
	v_mfma_f32_16x16x32_bf16 v[0:3], v[216:219], v[182:185], v[0:3]
	v_mfma_f32_16x16x32_bf16 v[56:59], v[198:201], v[162:165], v[56:59]
	v_mfma_f32_16x16x32_bf16 v[48:51], v[220:223], v[162:165], v[48:51]
	v_mfma_f32_16x16x32_bf16 v[40:43], v[198:201], v[170:173], v[40:43]
	v_mfma_f32_16x16x32_bf16 v[32:35], v[220:223], v[170:173], v[32:35]
	v_mfma_f32_16x16x32_bf16 v[24:27], v[198:201], v[178:181], v[24:27]
	v_mfma_f32_16x16x32_bf16 v[16:19], v[220:223], v[178:181], v[16:19]
	v_mfma_f32_16x16x32_bf16 v[8:11], v[198:201], v[190:193], v[8:11]
	v_mfma_f32_16x16x32_bf16 v[0:3], v[220:223], v[190:193], v[0:3]
	s_setprio 0
	s_add_i32 s38, s38, 2
	s_add_u32 s2, s2, 0x100
	s_addc_u32 s3, s3, 0
	s_add_u32 s36, s36, 0x100
	s_addc_u32 s37, s37, 0
	s_cmp_gt_u32 s38, 13
	s_barrier
	s_cbranch_scc0 .LBB0_124
	v_mul_f32_e32 v144, 0xbfb8aa3b, v124
	v_mul_f32_e32 v145, 0xbfb8aa3b, v125
	v_exp_f32_e32 v144, v144
	v_exp_f32_e32 v145, v145
	s_lshl_b32 s2, s31, 7
	v_lshl_add_u32 v141, s33, 8, v138
	v_add_f32_e32 v144, 1.0, v144
	v_add_f32_e32 v145, 1.0, v145
	v_rcp_f32_e32 v144, v144
	v_rcp_f32_e32 v145, v145
	s_ashr_i32 s3, s2, 31
	v_mov_b64_e32 v[136:137], s[88:89]
	s_movk_i32 s5, 0x1600
	v_pk_mul_f32 v[124:125], v[124:125], v[144:145]
	v_mad_i64_i32 v[142:143], s[16:17], v141, s5, v[136:137]
	v_pk_mul_f32 v[120:121], v[124:125], v[120:121]
	v_mul_f32_e32 v124, 0xbfb8aa3b, v126
	v_mul_f32_e32 v125, 0xbfb8aa3b, v127
	v_exp_f32_e32 v124, v124
	v_exp_f32_e32 v125, v125
	s_lshl_b64 s[2:3], s[2:3], 1
	v_lshl_add_u64 v[142:143], v[142:143], 0, s[2:3]
	v_add_f32_e32 v124, 1.0, v124
	v_add_f32_e32 v125, 1.0, v125
	v_rcp_f32_e32 v124, v124
	v_rcp_f32_e32 v125, v125
	v_lshl_add_u64 v[142:143], v[142:143], 0, s[0:1]
	v_lshl_add_u64 v[142:143], v[142:143], 0, v[188:189]
	v_cvt_pk_bf16_f32 v120, v120, v121
	v_pk_mul_f32 v[124:125], v[126:127], v[124:125]
	s_and_b64 vcc, exec, s[10:11]
	v_pk_mul_f32 v[122:123], v[124:125], v[122:123]
	s_mov_b32 s31, s8
	v_cvt_pk_bf16_f32 v121, v122, v123
	v_mul_f32_e32 v122, 0xbfb8aa3b, v116
	v_mul_f32_e32 v123, 0xbfb8aa3b, v117
	v_exp_f32_e32 v122, v122
	v_exp_f32_e32 v123, v123
	s_mov_b32 s33, s4
	v_add_f32_e32 v122, 1.0, v122
	v_add_f32_e32 v123, 1.0, v123
	v_rcp_f32_e32 v122, v122
	v_rcp_f32_e32 v123, v123
	s_nop 0
	v_pk_mul_f32 v[116:117], v[116:117], v[122:123]
	s_nop 0
	v_pk_mul_f32 v[112:113], v[116:117], v[112:113]
	v_mul_f32_e32 v116, 0xbfb8aa3b, v118
	v_mul_f32_e32 v117, 0xbfb8aa3b, v119
	v_exp_f32_e32 v116, v116
	v_exp_f32_e32 v117, v117
	v_cvt_pk_bf16_f32 v122, v112, v113
	v_add_f32_e32 v116, 1.0, v116
	v_add_f32_e32 v117, 1.0, v117
	v_rcp_f32_e32 v116, v116
	v_rcp_f32_e32 v117, v117
	s_nop 0
	v_pk_mul_f32 v[116:117], v[118:119], v[116:117]
	s_nop 0
	v_pk_mul_f32 v[114:115], v[116:117], v[114:115]
	s_nop 0
	v_cvt_pk_bf16_f32 v123, v114, v115
	v_mul_f32_e32 v114, 0xbfb8aa3b, v108
	v_mul_f32_e32 v115, 0xbfb8aa3b, v109
	v_exp_f32_e32 v114, v114
	v_exp_f32_e32 v115, v115
	s_nop 1
	v_permlane16_swap_b32 v120, v122
	v_permlane16_swap_b32 v121, v123
	global_store_dwordx4 v[142:143], v[120:123], off
	s_nop 1
	v_or_b32_e32 v112, 16, v141
	v_add_f32_e32 v114, 1.0, v114
	v_add_f32_e32 v115, 1.0, v115
	v_rcp_f32_e32 v114, v114
	v_rcp_f32_e32 v115, v115
	v_mad_i64_i32 v[112:113], s[16:17], v112, s5, v[136:137]
	v_lshl_add_u64 v[112:113], v[112:113], 0, s[2:3]
	v_pk_mul_f32 v[108:109], v[108:109], v[114:115]
	v_lshl_add_u64 v[112:113], v[112:113], 0, s[0:1]
	v_pk_mul_f32 v[104:105], v[108:109], v[104:105]
	v_mul_f32_e32 v108, 0xbfb8aa3b, v110
	v_mul_f32_e32 v109, 0xbfb8aa3b, v111
	v_exp_f32_e32 v108, v108
	v_exp_f32_e32 v109, v109
	v_lshl_add_u64 v[112:113], v[112:113], 0, v[188:189]
	v_cvt_pk_bf16_f32 v104, v104, v105
	v_add_f32_e32 v108, 1.0, v108
	v_add_f32_e32 v109, 1.0, v109
	v_rcp_f32_e32 v108, v108
	v_rcp_f32_e32 v109, v109
	s_nop 0
	v_pk_mul_f32 v[108:109], v[110:111], v[108:109]
	s_nop 0
	v_pk_mul_f32 v[106:107], v[108:109], v[106:107]
	s_nop 0
	v_cvt_pk_bf16_f32 v105, v106, v107
	v_mul_f32_e32 v106, 0xbfb8aa3b, v100
	v_mul_f32_e32 v107, 0xbfb8aa3b, v101
	v_exp_f32_e32 v106, v106
	v_exp_f32_e32 v107, v107
	v_add_f32_e32 v106, 1.0, v106
	v_add_f32_e32 v107, 1.0, v107
	v_rcp_f32_e32 v106, v106
	v_rcp_f32_e32 v107, v107
	s_nop 0
	v_pk_mul_f32 v[100:101], v[100:101], v[106:107]
	s_nop 0
	v_pk_mul_f32 v[96:97], v[100:101], v[96:97]
	v_mul_f32_e32 v100, 0xbfb8aa3b, v102
	v_mul_f32_e32 v101, 0xbfb8aa3b, v103
	v_exp_f32_e32 v100, v100
	v_exp_f32_e32 v101, v101
	v_cvt_pk_bf16_f32 v106, v96, v97
	v_add_f32_e32 v100, 1.0, v100
	v_add_f32_e32 v101, 1.0, v101
	v_rcp_f32_e32 v100, v100
	v_rcp_f32_e32 v101, v101
	s_nop 0
	v_pk_mul_f32 v[100:101], v[102:103], v[100:101]
	s_nop 0
	v_pk_mul_f32 v[98:99], v[100:101], v[98:99]
	s_nop 0
	v_cvt_pk_bf16_f32 v107, v98, v99
	v_mul_f32_e32 v98, 0xbfb8aa3b, v92
	v_mul_f32_e32 v99, 0xbfb8aa3b, v93
	v_exp_f32_e32 v98, v98
	v_exp_f32_e32 v99, v99
	s_nop 1
	v_permlane16_swap_b32 v104, v106
	v_permlane16_swap_b32 v105, v107
	global_store_dwordx4 v[112:113], v[104:107], off
	s_nop 1
	v_or_b32_e32 v96, 32, v141
	v_add_f32_e32 v98, 1.0, v98
	v_add_f32_e32 v99, 1.0, v99
	v_rcp_f32_e32 v98, v98
	v_rcp_f32_e32 v99, v99
	v_mad_i64_i32 v[96:97], s[16:17], v96, s5, v[136:137]
	v_lshl_add_u64 v[96:97], v[96:97], 0, s[2:3]
	v_pk_mul_f32 v[92:93], v[92:93], v[98:99]
	v_lshl_add_u64 v[96:97], v[96:97], 0, s[0:1]
	v_pk_mul_f32 v[88:89], v[92:93], v[88:89]
	v_mul_f32_e32 v92, 0xbfb8aa3b, v94
	v_mul_f32_e32 v93, 0xbfb8aa3b, v95
	v_exp_f32_e32 v92, v92
	v_exp_f32_e32 v93, v93
	v_lshl_add_u64 v[96:97], v[96:97], 0, v[188:189]
	v_cvt_pk_bf16_f32 v88, v88, v89
	v_add_f32_e32 v92, 1.0, v92
	v_add_f32_e32 v93, 1.0, v93
	v_rcp_f32_e32 v92, v92
	v_rcp_f32_e32 v93, v93
	s_nop 0
	v_pk_mul_f32 v[92:93], v[94:95], v[92:93]
	s_nop 0
	v_pk_mul_f32 v[90:91], v[92:93], v[90:91]
	s_nop 0
	v_cvt_pk_bf16_f32 v89, v90, v91
	v_mul_f32_e32 v90, 0xbfb8aa3b, v84
	v_mul_f32_e32 v91, 0xbfb8aa3b, v85
	v_exp_f32_e32 v90, v90
	v_exp_f32_e32 v91, v91
	v_add_f32_e32 v90, 1.0, v90
	v_add_f32_e32 v91, 1.0, v91
	v_rcp_f32_e32 v90, v90
	v_rcp_f32_e32 v91, v91
	s_nop 0
	v_pk_mul_f32 v[84:85], v[84:85], v[90:91]
	s_nop 0
	v_pk_mul_f32 v[80:81], v[84:85], v[80:81]
	v_mul_f32_e32 v84, 0xbfb8aa3b, v86
	v_mul_f32_e32 v85, 0xbfb8aa3b, v87
	v_exp_f32_e32 v84, v84
	v_exp_f32_e32 v85, v85
	v_cvt_pk_bf16_f32 v90, v80, v81
	v_add_f32_e32 v84, 1.0, v84
	v_add_f32_e32 v85, 1.0, v85
	v_rcp_f32_e32 v84, v84
	v_rcp_f32_e32 v85, v85
	s_nop 0
	v_pk_mul_f32 v[84:85], v[86:87], v[84:85]
	s_nop 0
	v_pk_mul_f32 v[82:83], v[84:85], v[82:83]
	s_nop 0
	v_cvt_pk_bf16_f32 v91, v82, v83
	v_mul_f32_e32 v82, 0xbfb8aa3b, v76
	v_mul_f32_e32 v83, 0xbfb8aa3b, v77
	v_exp_f32_e32 v82, v82
	v_exp_f32_e32 v83, v83
	s_nop 1
	v_permlane16_swap_b32 v88, v90
	v_permlane16_swap_b32 v89, v91
	global_store_dwordx4 v[96:97], v[88:91], off
	s_nop 1
	v_or_b32_e32 v80, 48, v141
	v_add_f32_e32 v82, 1.0, v82
	v_add_f32_e32 v83, 1.0, v83
	v_rcp_f32_e32 v82, v82
	v_rcp_f32_e32 v83, v83
	v_mad_i64_i32 v[80:81], s[16:17], v80, s5, v[136:137]
	v_lshl_add_u64 v[80:81], v[80:81], 0, s[2:3]
	v_pk_mul_f32 v[76:77], v[76:77], v[82:83]
	v_lshl_add_u64 v[80:81], v[80:81], 0, s[0:1]
	v_pk_mul_f32 v[72:73], v[76:77], v[72:73]
	v_mul_f32_e32 v76, 0xbfb8aa3b, v78
	v_mul_f32_e32 v77, 0xbfb8aa3b, v79
	v_exp_f32_e32 v76, v76
	v_exp_f32_e32 v77, v77
	v_lshl_add_u64 v[80:81], v[80:81], 0, v[188:189]
	v_cvt_pk_bf16_f32 v72, v72, v73
	v_add_f32_e32 v76, 1.0, v76
	v_add_f32_e32 v77, 1.0, v77
	v_rcp_f32_e32 v76, v76
	v_rcp_f32_e32 v77, v77
	s_nop 0
	v_pk_mul_f32 v[76:77], v[78:79], v[76:77]
	s_nop 0
	v_pk_mul_f32 v[74:75], v[76:77], v[74:75]
	s_nop 0
	v_cvt_pk_bf16_f32 v73, v74, v75
	v_mul_f32_e32 v74, 0xbfb8aa3b, v68
	v_mul_f32_e32 v75, 0xbfb8aa3b, v69
	v_exp_f32_e32 v74, v74
	v_exp_f32_e32 v75, v75
	v_add_f32_e32 v74, 1.0, v74
	v_add_f32_e32 v75, 1.0, v75
	v_rcp_f32_e32 v74, v74
	v_rcp_f32_e32 v75, v75
	s_nop 0
	v_pk_mul_f32 v[68:69], v[68:69], v[74:75]
	s_nop 0
	v_pk_mul_f32 v[64:65], v[68:69], v[64:65]
	v_mul_f32_e32 v68, 0xbfb8aa3b, v70
	v_mul_f32_e32 v69, 0xbfb8aa3b, v71
	v_exp_f32_e32 v68, v68
	v_exp_f32_e32 v69, v69
	v_cvt_pk_bf16_f32 v74, v64, v65
	v_add_f32_e32 v68, 1.0, v68
	v_add_f32_e32 v69, 1.0, v69
	v_rcp_f32_e32 v68, v68
	v_rcp_f32_e32 v69, v69
	s_nop 0
	v_pk_mul_f32 v[68:69], v[70:71], v[68:69]
	s_nop 0
	v_pk_mul_f32 v[66:67], v[68:69], v[66:67]
	s_nop 0
	v_cvt_pk_bf16_f32 v75, v66, v67
	v_mul_f32_e32 v66, 0xbfb8aa3b, v60
	v_mul_f32_e32 v67, 0xbfb8aa3b, v61
	v_exp_f32_e32 v66, v66
	v_exp_f32_e32 v67, v67
	s_nop 1
	v_permlane16_swap_b32 v72, v74
	v_permlane16_swap_b32 v73, v75
	global_store_dwordx4 v[80:81], v[72:75], off
	s_nop 1
	v_add_u32_e32 v64, 0x80, v141
	v_add_f32_e32 v66, 1.0, v66
	v_add_f32_e32 v67, 1.0, v67
	v_rcp_f32_e32 v66, v66
	v_rcp_f32_e32 v67, v67
	v_mad_i64_i32 v[64:65], s[16:17], v64, s5, v[136:137]
	v_lshl_add_u64 v[64:65], v[64:65], 0, s[2:3]
	v_pk_mul_f32 v[60:61], v[60:61], v[66:67]
	v_lshl_add_u64 v[64:65], v[64:65], 0, s[0:1]
	v_pk_mul_f32 v[56:57], v[60:61], v[56:57]
	v_mul_f32_e32 v60, 0xbfb8aa3b, v62
	v_mul_f32_e32 v61, 0xbfb8aa3b, v63
	v_exp_f32_e32 v60, v60
	v_exp_f32_e32 v61, v61
	v_lshl_add_u64 v[64:65], v[64:65], 0, v[188:189]
	v_cvt_pk_bf16_f32 v56, v56, v57
	v_add_f32_e32 v60, 1.0, v60
	v_add_f32_e32 v61, 1.0, v61
	v_rcp_f32_e32 v60, v60
	v_rcp_f32_e32 v61, v61
	s_nop 0
	v_pk_mul_f32 v[60:61], v[62:63], v[60:61]
	s_nop 0
	v_pk_mul_f32 v[58:59], v[60:61], v[58:59]
	s_nop 0
	v_cvt_pk_bf16_f32 v57, v58, v59
	v_mul_f32_e32 v58, 0xbfb8aa3b, v52
	v_mul_f32_e32 v59, 0xbfb8aa3b, v53
	v_exp_f32_e32 v58, v58
	v_exp_f32_e32 v59, v59
	v_add_f32_e32 v58, 1.0, v58
	v_add_f32_e32 v59, 1.0, v59
	v_rcp_f32_e32 v58, v58
	v_rcp_f32_e32 v59, v59
	s_nop 0
	v_pk_mul_f32 v[52:53], v[52:53], v[58:59]
	s_nop 0
	v_pk_mul_f32 v[48:49], v[52:53], v[48:49]
	v_mul_f32_e32 v52, 0xbfb8aa3b, v54
	v_mul_f32_e32 v53, 0xbfb8aa3b, v55
	v_exp_f32_e32 v52, v52
	v_exp_f32_e32 v53, v53
	v_cvt_pk_bf16_f32 v58, v48, v49
	v_add_f32_e32 v52, 1.0, v52
	v_add_f32_e32 v53, 1.0, v53
	v_rcp_f32_e32 v52, v52
	v_rcp_f32_e32 v53, v53
	s_nop 0
	v_pk_mul_f32 v[52:53], v[54:55], v[52:53]
	s_nop 0
	v_pk_mul_f32 v[50:51], v[52:53], v[50:51]
	s_nop 0
	v_cvt_pk_bf16_f32 v59, v50, v51
	v_mul_f32_e32 v50, 0xbfb8aa3b, v44
	v_mul_f32_e32 v51, 0xbfb8aa3b, v45
	v_exp_f32_e32 v50, v50
	v_exp_f32_e32 v51, v51
	s_nop 1
	v_permlane16_swap_b32 v56, v58
	v_permlane16_swap_b32 v57, v59
	global_store_dwordx4 v[64:65], v[56:59], off
	s_nop 1
	v_add_u32_e32 v48, 0x90, v141
	v_add_f32_e32 v50, 1.0, v50
	v_add_f32_e32 v51, 1.0, v51
	v_rcp_f32_e32 v50, v50
	v_rcp_f32_e32 v51, v51
	v_mad_i64_i32 v[48:49], s[16:17], v48, s5, v[136:137]
	v_lshl_add_u64 v[48:49], v[48:49], 0, s[2:3]
	v_pk_mul_f32 v[44:45], v[44:45], v[50:51]
	v_lshl_add_u64 v[48:49], v[48:49], 0, s[0:1]
	v_pk_mul_f32 v[40:41], v[44:45], v[40:41]
	v_mul_f32_e32 v44, 0xbfb8aa3b, v46
	v_mul_f32_e32 v45, 0xbfb8aa3b, v47
	v_exp_f32_e32 v44, v44
	v_exp_f32_e32 v45, v45
	v_lshl_add_u64 v[48:49], v[48:49], 0, v[188:189]
	v_cvt_pk_bf16_f32 v40, v40, v41
	v_add_f32_e32 v44, 1.0, v44
	v_add_f32_e32 v45, 1.0, v45
	v_rcp_f32_e32 v44, v44
	v_rcp_f32_e32 v45, v45
	s_nop 0
	v_pk_mul_f32 v[44:45], v[46:47], v[44:45]
	s_nop 0
	v_pk_mul_f32 v[42:43], v[44:45], v[42:43]
	s_nop 0
	v_cvt_pk_bf16_f32 v41, v42, v43
	v_mul_f32_e32 v42, 0xbfb8aa3b, v36
	v_mul_f32_e32 v43, 0xbfb8aa3b, v37
	v_exp_f32_e32 v42, v42
	v_exp_f32_e32 v43, v43
	v_add_f32_e32 v42, 1.0, v42
	v_add_f32_e32 v43, 1.0, v43
	v_rcp_f32_e32 v42, v42
	v_rcp_f32_e32 v43, v43
	s_nop 0
	v_pk_mul_f32 v[36:37], v[36:37], v[42:43]
	s_nop 0
	v_pk_mul_f32 v[32:33], v[36:37], v[32:33]
	v_mul_f32_e32 v36, 0xbfb8aa3b, v38
	v_mul_f32_e32 v37, 0xbfb8aa3b, v39
	v_exp_f32_e32 v36, v36
	v_exp_f32_e32 v37, v37
	v_cvt_pk_bf16_f32 v42, v32, v33
	v_add_f32_e32 v36, 1.0, v36
	v_add_f32_e32 v37, 1.0, v37
	v_rcp_f32_e32 v36, v36
	v_rcp_f32_e32 v37, v37
	s_nop 0
	v_pk_mul_f32 v[36:37], v[38:39], v[36:37]
	s_nop 0
	v_pk_mul_f32 v[34:35], v[36:37], v[34:35]
	s_nop 0
	v_cvt_pk_bf16_f32 v43, v34, v35
	v_mul_f32_e32 v34, 0xbfb8aa3b, v28
	v_mul_f32_e32 v35, 0xbfb8aa3b, v29
	v_exp_f32_e32 v34, v34
	v_exp_f32_e32 v35, v35
	s_nop 1
	v_permlane16_swap_b32 v40, v42
	v_permlane16_swap_b32 v41, v43
	global_store_dwordx4 v[48:49], v[40:43], off
	s_nop 1
	v_add_u32_e32 v32, 0xa0, v141
	v_add_f32_e32 v34, 1.0, v34
	v_add_f32_e32 v35, 1.0, v35
	v_rcp_f32_e32 v34, v34
	v_rcp_f32_e32 v35, v35
	v_mad_i64_i32 v[32:33], s[16:17], v32, s5, v[136:137]
	v_lshl_add_u64 v[32:33], v[32:33], 0, s[2:3]
	v_pk_mul_f32 v[28:29], v[28:29], v[34:35]
	v_lshl_add_u64 v[32:33], v[32:33], 0, s[0:1]
	v_pk_mul_f32 v[24:25], v[28:29], v[24:25]
	v_mul_f32_e32 v28, 0xbfb8aa3b, v30
	v_mul_f32_e32 v29, 0xbfb8aa3b, v31
	v_exp_f32_e32 v28, v28
	v_exp_f32_e32 v29, v29
	v_lshl_add_u64 v[32:33], v[32:33], 0, v[188:189]
	v_cvt_pk_bf16_f32 v24, v24, v25
	v_add_f32_e32 v28, 1.0, v28
	v_add_f32_e32 v29, 1.0, v29
	v_rcp_f32_e32 v28, v28
	v_rcp_f32_e32 v29, v29
	s_nop 0
	v_pk_mul_f32 v[28:29], v[30:31], v[28:29]
	s_nop 0
	v_pk_mul_f32 v[26:27], v[28:29], v[26:27]
	s_nop 0
	v_cvt_pk_bf16_f32 v25, v26, v27
	v_mul_f32_e32 v26, 0xbfb8aa3b, v20
	v_mul_f32_e32 v27, 0xbfb8aa3b, v21
	v_exp_f32_e32 v26, v26
	v_exp_f32_e32 v27, v27
	v_add_f32_e32 v26, 1.0, v26
	v_add_f32_e32 v27, 1.0, v27
	v_rcp_f32_e32 v26, v26
	v_rcp_f32_e32 v27, v27
	s_nop 0
	v_pk_mul_f32 v[20:21], v[20:21], v[26:27]
	s_nop 0
	v_pk_mul_f32 v[16:17], v[20:21], v[16:17]
	v_mul_f32_e32 v20, 0xbfb8aa3b, v22
	v_mul_f32_e32 v21, 0xbfb8aa3b, v23
	v_exp_f32_e32 v20, v20
	v_exp_f32_e32 v21, v21
	v_cvt_pk_bf16_f32 v26, v16, v17
	v_add_f32_e32 v20, 1.0, v20
	v_add_f32_e32 v21, 1.0, v21
	v_rcp_f32_e32 v20, v20
	v_rcp_f32_e32 v21, v21
	s_nop 0
	v_pk_mul_f32 v[20:21], v[22:23], v[20:21]
	s_nop 0
	v_pk_mul_f32 v[18:19], v[20:21], v[18:19]
	s_nop 0
	v_cvt_pk_bf16_f32 v27, v18, v19
	v_mul_f32_e32 v18, 0xbfb8aa3b, v12
	v_mul_f32_e32 v19, 0xbfb8aa3b, v13
	v_exp_f32_e32 v18, v18
	v_exp_f32_e32 v19, v19
	s_nop 1
	v_permlane16_swap_b32 v24, v26
	v_permlane16_swap_b32 v25, v27
	global_store_dwordx4 v[32:33], v[24:27], off
	s_nop 1
	v_add_u32_e32 v16, 0xb0, v141
	v_add_f32_e32 v18, 1.0, v18
	v_add_f32_e32 v19, 1.0, v19
	v_rcp_f32_e32 v18, v18
	v_rcp_f32_e32 v19, v19
	v_mad_i64_i32 v[16:17], s[16:17], v16, s5, v[136:137]
	v_lshl_add_u64 v[16:17], v[16:17], 0, s[2:3]
	v_pk_mul_f32 v[12:13], v[12:13], v[18:19]
	v_lshl_add_u64 v[16:17], v[16:17], 0, s[0:1]
	v_pk_mul_f32 v[8:9], v[12:13], v[8:9]
	v_mul_f32_e32 v12, 0xbfb8aa3b, v14
	v_mul_f32_e32 v13, 0xbfb8aa3b, v15
	v_exp_f32_e32 v12, v12
	v_exp_f32_e32 v13, v13
	v_lshl_add_u64 v[16:17], v[16:17], 0, v[188:189]
	v_cvt_pk_bf16_f32 v8, v8, v9
	v_add_f32_e32 v12, 1.0, v12
	v_add_f32_e32 v13, 1.0, v13
	v_rcp_f32_e32 v12, v12
	v_rcp_f32_e32 v13, v13
	s_mov_b64 s[16:17], s[14:15]
	s_mov_b64 s[2:3], s[12:13]
	v_pk_mul_f32 v[12:13], v[14:15], v[12:13]
	s_nop 0
	v_pk_mul_f32 v[10:11], v[12:13], v[10:11]
	s_nop 0
	v_cvt_pk_bf16_f32 v9, v10, v11
	v_mul_f32_e32 v10, 0xbfb8aa3b, v4
	v_mul_f32_e32 v11, 0xbfb8aa3b, v5
	v_exp_f32_e32 v10, v10
	v_exp_f32_e32 v11, v11
	v_add_f32_e32 v10, 1.0, v10
	v_add_f32_e32 v11, 1.0, v11
	v_rcp_f32_e32 v10, v10
	v_rcp_f32_e32 v11, v11
	s_nop 0
	v_pk_mul_f32 v[4:5], v[4:5], v[10:11]
	s_nop 0
	v_pk_mul_f32 v[0:1], v[4:5], v[0:1]
	v_mul_f32_e32 v4, 0xbfb8aa3b, v6
	v_mul_f32_e32 v5, 0xbfb8aa3b, v7
	v_exp_f32_e32 v4, v4
	v_exp_f32_e32 v5, v5
	v_cvt_pk_bf16_f32 v10, v0, v1
	v_add_f32_e32 v4, 1.0, v4
	v_add_f32_e32 v5, 1.0, v5
	v_rcp_f32_e32 v4, v4
	v_rcp_f32_e32 v5, v5
	s_nop 0
	v_pk_mul_f32 v[4:5], v[6:7], v[4:5]
	s_nop 0
	v_pk_mul_f32 v[2:3], v[4:5], v[2:3]
	s_nop 0
	v_cvt_pk_bf16_f32 v11, v2, v3
	s_nop 1
	v_permlane16_swap_b32 v8, v10
	v_permlane16_swap_b32 v9, v11
	global_store_dwordx4 v[16:17], v[8:11], off
	s_nop 1
	s_cbranch_vccz .LBB0_121
	s_waitcnt vmcnt(0)
	s_cmpk_gt_u32 s20, 0xff
	s_mov_b32 s28, 0x8000
	s_movk_i32 s29, 0xc0
	s_mov_b32 s30, 0x800000
	s_movk_i32 s31, 0x7fff
	s_movk_i32 s33, 0x1800
	s_cbranch_scc1 .LBB0_128
	s_barrier
